# filter-MLP layer-1 weight loads batched; ctx filter items remapped to lightly loaded blocks
# speedup vs baseline: 1.1528x; 1.0065x over previous
.LBB0_36:
	s_or_b64 exec, exec, s[62:63]
	s_and_b64 s[10:11], s[42:43], exec
	s_cselect_b32 s10, 0x2100, 0
	s_waitcnt lgkmcnt(0)
	s_add_u32 s10, s58, s10
	s_addc_u32 s11, s59, 0
	s_and_b64 s[12:13], s[42:43], exec
	s_cselect_b32 s12, 64, 0
	s_lshl_b32 s58, s12, 2
	s_add_u32 s12, s56, s58
	s_addc_u32 s13, s57, 0
	s_add_u32 s14, s60, s58
	s_addc_u32 s15, s61, 0
	s_barrier
	global_load_dword v8, v98, s[14:15]
	global_load_dword v4, v98, s[12:13]
	global_load_dword v108, v98, s[10:11]
	global_load_dword v109, v98, s[10:11] offset:256
	global_load_dword v110, v98, s[10:11] offset:512
	global_load_dword v111, v98, s[10:11] offset:768
	global_load_dword v112, v98, s[10:11] offset:1024
	global_load_dword v113, v98, s[10:11] offset:1280
	global_load_dword v114, v98, s[10:11] offset:1536
	global_load_dword v115, v98, s[10:11] offset:1792
	global_load_dword v116, v98, s[10:11] offset:2048
	global_load_dword v117, v98, s[10:11] offset:2304
	global_load_dword v118, v98, s[10:11] offset:2560
	global_load_dword v119, v98, s[10:11] offset:2816
	global_load_dword v120, v98, s[10:11] offset:3072
	global_load_dword v121, v98, s[10:11] offset:3328
	global_load_dword v122, v98, s[10:11] offset:3584
	global_load_dword v123, v98, s[10:11] offset:3840
	global_load_dword v124, v50, s[10:11]
	global_load_dword v125, v51, s[10:11]
	global_load_dword v126, v52, s[10:11]
	global_load_dword v127, v53, s[10:11]
	global_load_dword v128, v54, s[10:11]
	global_load_dword v129, v55, s[10:11]
	global_load_dword v130, v56, s[10:11]
	global_load_dword v132, v57, s[10:11]
	global_load_dword v133, v58, s[10:11]
	global_load_dword v134, v59, s[10:11]
	global_load_dword v135, v60, s[10:11]
	global_load_dword v136, v61, s[10:11]
	global_load_dword v137, v62, s[10:11]
	global_load_dword v138, v63, s[10:11]
	global_load_dword v139, v64, s[10:11]
	global_load_dword v140, v65, s[10:11]
	global_load_dword v141, v66, s[10:11]
	ds_read_b128 v[10:13], v99
	ds_read_b128 v[14:17], v99 offset:16
	ds_read_b128 v[18:21], v99 offset:32
	ds_read_b128 v[22:25], v99 offset:48
	ds_read_b128 v[26:29], v99 offset:64
	ds_read_b96 v[30:32], v99 offset:80
	ds_read2_b32 v[34:35], v99 offset0:23 offset1:24
	ds_read2_b32 v[142:143], v99 offset0:25 offset1:26
	ds_read2_b32 v[144:145], v99 offset0:27 offset1:28
	s_waitcnt vmcnt(0) lgkmcnt(0)
	v_fmac_f32_e32 v4, v10, v108
	v_fmac_f32_e32 v4, v11, v109
	v_fmac_f32_e32 v4, v12, v110
	v_fmac_f32_e32 v4, v13, v111
	ds_read2_b32 v[10:11], v99 offset0:29 offset1:30
	ds_read2_b32 v[12:13], v99 offset0:31 offset1:32
	v_fmac_f32_e32 v4, v14, v112
	v_fmac_f32_e32 v4, v15, v113
	v_fmac_f32_e32 v4, v16, v114
	v_fmac_f32_e32 v4, v17, v115
	v_fmac_f32_e32 v4, v18, v116
	v_fmac_f32_e32 v4, v19, v117
	v_fmac_f32_e32 v4, v20, v118
	v_fmac_f32_e32 v4, v21, v119
	v_fmac_f32_e32 v4, v22, v120
	v_fmac_f32_e32 v4, v23, v121
	v_fmac_f32_e32 v4, v24, v122
	v_fmac_f32_e32 v4, v25, v123
	v_fmac_f32_e32 v4, v26, v124
	v_fmac_f32_e32 v4, v27, v125
	v_fmac_f32_e32 v4, v28, v126
	v_fmac_f32_e32 v4, v29, v127
	v_fmac_f32_e32 v4, v30, v128
	v_fmac_f32_e32 v4, v31, v129
	v_fmac_f32_e32 v4, v32, v130
	v_pk_mul_f32 v[34:35], v[34:35], v[132:133]
	s_nop 0
	v_add_f32_e32 v4, v4, v34
	v_add_f32_e32 v4, v4, v35
	v_pk_mul_f32 v[142:143], v[142:143], v[134:135]
	s_nop 0
	v_add_f32_e32 v4, v4, v142
	v_add_f32_e32 v4, v4, v143
	v_pk_mul_f32 v[144:145], v[144:145], v[136:137]
	s_nop 0
	v_add_f32_e32 v4, v4, v144
	v_add_f32_e32 v4, v4, v145
	s_waitcnt lgkmcnt(0)
	v_pk_mul_f32 v[10:11], v[10:11], v[138:139]
	s_nop 0
	v_add_f32_e32 v4, v4, v10
	v_add_f32_e32 v4, v4, v11
	v_pk_mul_f32 v[12:13], v[12:13], v[140:141]
	s_nop 0
	v_add_f32_e32 v4, v4, v12
	v_add_f32_e32 v4, v4, v13
	v_mul_f32_e32 v9, v8, v4
	v_and_b32_e32 v10, 0x7fffffff, v9
	v_cmp_nlt_f32_e64 s[10:11], |v9|, s77
	s_and_saveexec_b64 s[12:13], s[10:11]
	s_xor_b64 s[56:57], exec, s[12:13]
	s_cbranch_execz .LBB0_38
	v_lshrrev_b32_e32 v4, 23, v10
	v_add_u32_e32 v4, 0xffffff88, v4
	v_cmp_lt_u32_e32 vcc, 63, v4
	s_nop 1
	v_cndmask_b32_e32 v11, 0, v103, vcc
	v_add_u32_e32 v4, v11, v4
	v_cmp_lt_u32_e64 s[10:11], 31, v4
	s_nop 1
	v_cndmask_b32_e64 v11, 0, v104, s[10:11]
	v_add_u32_e32 v4, v11, v4
	v_cmp_lt_u32_e64 s[12:13], 31, v4
	s_nop 1
	v_cndmask_b32_e64 v11, 0, v104, s[12:13]
	v_add_u32_e32 v11, v11, v4
	v_and_b32_e32 v4, 0x7fffff, v10
	v_or_b32_e32 v24, 0x800000, v4
	v_mad_u64_u32 v[12:13], s[14:15], v24, s78, 0
	v_mov_b32_e32 v4, v13
	v_mad_u64_u32 v[14:15], s[14:15], v24, s79, v[4:5]
	v_mov_b32_e32 v4, v15
	v_mad_u64_u32 v[16:17], s[14:15], v24, s80, v[4:5]
	v_mov_b32_e32 v4, v17
	v_mad_u64_u32 v[18:19], s[14:15], v24, s81, v[4:5]
	v_mov_b32_e32 v4, v19
	v_mad_u64_u32 v[20:21], s[14:15], v24, s82, v[4:5]
	v_mov_b32_e32 v4, v21
	v_mad_u64_u32 v[22:23], s[14:15], v24, s83, v[4:5]
	v_mov_b32_e32 v4, v23
	v_mad_u64_u32 v[24:25], s[14:15], v24, s84, v[4:5]
	v_cndmask_b32_e32 v13, v22, v18, vcc
	v_cndmask_b32_e32 v4, v24, v20, vcc
	v_cndmask_b32_e32 v17, v25, v22, vcc
	v_cndmask_b32_e64 v15, v4, v13, s[10:11]
	v_cndmask_b32_e64 v4, v17, v4, s[10:11]
	v_cndmask_b32_e32 v17, v20, v16, vcc
	v_cndmask_b32_e64 v13, v13, v17, s[10:11]
	v_sub_u32_e32 v19, 32, v11
	v_cmp_eq_u32_e64 s[14:15], 0, v11
	v_cndmask_b32_e32 v11, v18, v14, vcc
	v_cndmask_b32_e64 v4, v4, v15, s[12:13]
	v_cndmask_b32_e64 v15, v15, v13, s[12:13]
	v_cndmask_b32_e64 v14, v17, v11, s[10:11]
	v_alignbit_b32 v20, v4, v15, v19
	v_cndmask_b32_e64 v13, v13, v14, s[12:13]
	v_cndmask_b32_e64 v4, v20, v4, s[14:15]
	v_alignbit_b32 v17, v15, v13, v19
	v_cndmask_b32_e32 v12, v16, v12, vcc
	v_cndmask_b32_e64 v15, v17, v15, s[14:15]
	v_bfe_u32 v20, v4, 29, 1
	v_cndmask_b32_e64 v11, v11, v12, s[10:11]
	v_alignbit_b32 v17, v4, v15, 30
	v_sub_u32_e32 v21, 0, v20
	v_cndmask_b32_e64 v11, v14, v11, s[12:13]
	v_xor_b32_e32 v17, v17, v21
	v_alignbit_b32 v12, v13, v11, v19
	v_cndmask_b32_e64 v12, v12, v13, s[14:15]
	v_ffbh_u32_e32 v14, v17
	v_alignbit_b32 v13, v15, v12, 30
	v_min_u32_e32 v14, 32, v14
	v_alignbit_b32 v11, v12, v11, 30
	v_xor_b32_e32 v13, v13, v21
	v_sub_u32_e32 v15, 31, v14
	v_xor_b32_e32 v11, v11, v21
	v_alignbit_b32 v16, v17, v13, v15
	v_alignbit_b32 v11, v13, v11, v15
	v_alignbit_b32 v12, v16, v11, 9
	v_ffbh_u32_e32 v13, v12
	v_min_u32_e32 v13, 32, v13
	v_lshrrev_b32_e32 v18, 29, v4
	v_not_b32_e32 v15, v13
	v_alignbit_b32 v11, v12, v11, v15
	v_lshlrev_b32_e32 v12, 31, v18
	v_or_b32_e32 v15, 0x33000000, v12
	v_add_lshl_u32 v13, v13, v14, 23
	v_lshrrev_b32_e32 v11, 9, v11
	v_sub_u32_e32 v13, v15, v13
	v_or_b32_e32 v12, 0.5, v12
	v_lshlrev_b32_e32 v14, 23, v14
	v_or_b32_e32 v11, v13, v11
	v_lshrrev_b32_e32 v13, 9, v16
	v_sub_u32_e32 v12, v12, v14
	v_or_b32_e32 v12, v13, v12
	v_mul_f32_e32 v13, 0x3fc90fda, v12
	v_fma_f32 v14, v12, s85, -v13
	v_fmac_f32_e32 v14, 0x33a22168, v12
	v_fmac_f32_e32 v14, 0x3fc90fda, v11
	v_lshrrev_b32_e32 v4, 30, v4
	v_add_f32_e32 v11, v13, v14
	v_add_u32_e32 v4, v20, v4

.LBB0_50:
	v_add_u32_e32 v26, 0xffff9800, v16
	v_ashrrev_i32_e32 v27, 31, v26
	v_ashrrev_i32_e32 v17, 31, v16
	v_lshl_add_u64 v[26:27], v[26:27], 2, s[42:43]
	v_lshl_add_u64 v[116:117], v[16:17], 2, s[42:43]
	global_load_dword v40, v[12:13], off
	global_load_dword v38, v[14:15], off
	global_load_dword v42, v[26:27], off
	global_load_dword v36, v[116:117], off
	v_add_u32_e32 v26, 0xffffa000, v16
	v_ashrrev_i32_e32 v27, 31, v26
	v_lshl_add_u64 v[26:27], v[26:27], 2, s[42:43]
	global_load_dword v44, v[26:27], off
	v_add_u32_e32 v26, 0xffffa800, v16
	v_ashrrev_i32_e32 v27, 31, v26
	v_lshl_add_u64 v[26:27], v[26:27], 2, s[42:43]
	global_load_dword v152, v[26:27], off
	v_add_u32_e32 v26, 0xffffb000, v16
	v_ashrrev_i32_e32 v27, 31, v26
	v_lshl_add_u64 v[26:27], v[26:27], 2, s[42:43]
	global_load_dword v4, v[26:27], off
	v_add_u32_e32 v26, 0xffffb800, v16
	v_add_u32_e32 v28, 0xffffc000, v16
	v_ashrrev_i32_e32 v27, 31, v26
	v_ashrrev_i32_e32 v29, 31, v28
	v_lshl_add_u64 v[26:27], v[26:27], 2, s[42:43]
	v_lshl_add_u64 v[28:29], v[28:29], 2, s[42:43]
	global_load_dword v26, v[26:27], off
	v_add_u32_e32 v30, 0xffffd000, v16
	global_load_dword v27, v[28:29], off
	v_add_u32_e32 v28, 0xffffc800, v16
	v_ashrrev_i32_e32 v29, 31, v28
	v_ashrrev_i32_e32 v31, 31, v30
	v_lshl_add_u64 v[28:29], v[28:29], 2, s[42:43]
	v_lshl_add_u64 v[30:31], v[30:31], 2, s[42:43]
	global_load_dword v28, v[28:29], off
	v_add_u32_e32 v32, 0xffffe000, v16
	global_load_dword v29, v[30:31], off
	v_add_u32_e32 v30, 0xffffd800, v16
	v_ashrrev_i32_e32 v31, 31, v30
	v_ashrrev_i32_e32 v33, 31, v32
	v_lshl_add_u64 v[30:31], v[30:31], 2, s[42:43]
	v_lshl_add_u64 v[32:33], v[32:33], 2, s[42:43]
	global_load_dword v30, v[30:31], off
	v_add_u32_e32 v34, 0xfffff000, v16
	global_load_dword v31, v[32:33], off
	v_add_u32_e32 v32, 0xffffe800, v16
	v_ashrrev_i32_e32 v33, 31, v32
	v_ashrrev_i32_e32 v35, 31, v34
	v_lshl_add_u64 v[32:33], v[32:33], 2, s[42:43]
	v_lshl_add_u64 v[34:35], v[34:35], 2, s[42:43]
	global_load_dword v32, v[32:33], off
	v_mov_b32_e32 v17, s2
	global_load_dword v33, v[34:35], off
	v_add_u32_e32 v34, 0xfffff800, v16
	v_ashrrev_i32_e32 v35, 31, v34
	v_lshl_add_u64 v[34:35], v[34:35], 2, s[42:43]
	global_load_dword v34, v[34:35], off
	ds_read_b128 v[116:119], v17
	ds_read_b128 v[120:123], v17 offset:16
	ds_read_b128 v[124:127], v17 offset:32
	ds_read_b128 v[128:131], v17 offset:48
	ds_read_b128 v[132:135], v17 offset:272
	ds_read_b128 v[136:139], v17 offset:256
	s_waitcnt lgkmcnt(5)
	v_mov_b32_e32 v140, v116
	v_mov_b32_e32 v116, v118
	s_add_i32 s2, s2, 64
	s_add_i32 s3, s3, 16
	s_waitcnt lgkmcnt(0)
	v_mov_b32_e32 v141, v136
	v_mov_b32_e32 v136, v117
	v_mov_b32_e32 v117, v138
	v_mov_b32_e32 v138, v119
	v_add_u32_e32 v16, 0x8000, v16
	v_lshl_add_u64 v[14:15], v[14:15], 0, s[38:39]
	v_lshl_add_u64 v[12:13], v[12:13], 0, s[38:39]
	s_cmp_lt_u32 s3, 48
	s_waitcnt vmcnt(15)
	v_pk_fma_f32 v[20:21], v[40:41], v[140:141], v[20:21] op_sel_hi:[0,1,1]
	s_waitcnt vmcnt(14)
	v_pk_fma_f32 v[20:21], v[38:39], v[136:137], v[20:21] op_sel_hi:[0,1,1]
	s_waitcnt vmcnt(13)
	v_pk_fma_f32 v[20:21], v[42:43], v[116:117], v[20:21] op_sel_hi:[0,1,1]
	v_mov_b32_e32 v116, v120
	v_mov_b32_e32 v117, v132
	v_mov_b32_e32 v132, v121
	s_waitcnt vmcnt(11)
	v_pk_fma_f32 v[20:21], v[44:45], v[138:139], v[20:21] op_sel_hi:[0,1,1]
	s_waitcnt vmcnt(10)
	v_pk_fma_f32 v[160:161], v[152:153], v[116:117], v[20:21] op_sel_hi:[0,1,1]
	ds_read_b128 v[116:119], v17 offset:528
	ds_read_b128 v[136:139], v17 offset:784
	ds_read_b128 v[140:143], v17 offset:512
	ds_read_b128 v[144:147], v17 offset:768
	s_waitcnt lgkmcnt(1)
	v_mov_b32_e32 v20, v140
	s_waitcnt lgkmcnt(0)
	v_mov_b32_e32 v21, v144
	v_pk_fma_f32 v[20:21], v[40:41], v[20:21], v[22:23] op_sel_hi:[0,1,1]
	v_mov_b32_e32 v144, v141
	v_pk_fma_f32 v[20:21], v[38:39], v[144:145], v[20:21] op_sel_hi:[0,1,1]
	v_mov_b32_e32 v22, v142
	v_mov_b32_e32 v23, v146
	v_pk_fma_f32 v[20:21], v[42:43], v[22:23], v[20:21] op_sel_hi:[0,1,1]
	v_mov_b32_e32 v146, v143
	v_pk_fma_f32 v[20:21], v[44:45], v[146:147], v[20:21] op_sel_hi:[0,1,1]
	v_mov_b32_e32 v22, v116
	v_mov_b32_e32 v23, v136
	v_pk_fma_f32 v[162:163], v[152:153], v[22:23], v[20:21] op_sel_hi:[0,1,1]
	ds_read_b128 v[140:143], v17 offset:1040
	ds_read_b128 v[144:147], v17 offset:1296
	ds_read_b128 v[20:23], v17 offset:1024
	ds_read_b128 v[148:151], v17 offset:1280
	v_mov_b32_e32 v136, v117
	s_waitcnt lgkmcnt(1)
	v_mov_b32_e32 v154, v20
	s_waitcnt lgkmcnt(0)
	v_mov_b32_e32 v155, v148
	v_pk_fma_f32 v[24:25], v[40:41], v[154:155], v[24:25] op_sel_hi:[0,1,1]
	v_mov_b32_e32 v148, v21
	v_pk_fma_f32 v[20:21], v[38:39], v[148:149], v[24:25] op_sel_hi:[0,1,1]
	v_mov_b32_e32 v24, v22
	v_mov_b32_e32 v25, v150
	v_pk_fma_f32 v[20:21], v[42:43], v[24:25], v[20:21] op_sel_hi:[0,1,1]
	v_mov_b32_e32 v150, v23
	v_pk_fma_f32 v[20:21], v[44:45], v[150:151], v[20:21] op_sel_hi:[0,1,1]
	v_mov_b32_e32 v22, v140
	v_mov_b32_e32 v23, v144
	v_pk_fma_f32 v[164:165], v[152:153], v[22:23], v[20:21] op_sel_hi:[0,1,1]
	ds_read_b128 v[20:23], v17 offset:1552
	ds_read_b128 v[148:151], v17 offset:1808
	s_waitcnt vmcnt(9)
	v_mov_b32_e32 v153, v4
	v_mov_b32_e32 v144, v141
	s_waitcnt lgkmcnt(1)
	v_mul_f32_e32 v20, v152, v20
	s_waitcnt lgkmcnt(0)
	v_pk_mul_f32 v[140:141], v[152:153], v[148:149]
	ds_read_b128 v[152:155], v17 offset:1536
	ds_read_b128 v[156:159], v17 offset:1792
	v_mul_f32_e32 v120, v4, v21
	v_mov_b32_e32 v21, v140
	s_waitcnt vmcnt(8)
	v_mul_f32_e32 v140, v26, v22
	s_waitcnt lgkmcnt(1)
	v_mov_b32_e32 v24, v152
	s_waitcnt lgkmcnt(0)
	v_mov_b32_e32 v25, v156
	v_pk_fma_f32 v[18:19], v[40:41], v[24:25], v[18:19] op_sel_hi:[0,1,1]
	v_mov_b32_e32 v156, v153
	v_pk_fma_f32 v[18:19], v[38:39], v[156:157], v[18:19] op_sel_hi:[0,1,1]
	v_mov_b32_e32 v24, v154
	v_mov_b32_e32 v25, v158
	v_pk_fma_f32 v[18:19], v[42:43], v[24:25], v[18:19] op_sel_hi:[0,1,1]
	v_mov_b32_e32 v158, v155
	v_pk_fma_f32 v[18:19], v[44:45], v[158:159], v[18:19] op_sel_hi:[0,1,1]
	v_pk_add_f32 v[156:157], v[18:19], v[20:21]
	ds_read_b128 v[18:21], v17 offset:1568
	s_waitcnt vmcnt(7)
	v_mul_f32_e32 v158, v27, v23
	ds_read_b128 v[22:25], v17 offset:1824
	v_mov_b32_e32 v38, v27
	v_pk_mul_f32 v[166:167], v[26:27], v[150:151]
	s_waitcnt vmcnt(6) lgkmcnt(1)
	v_mul_f32_e32 v168, v28, v18
	s_waitcnt vmcnt(5)
	v_mul_f32_e32 v170, v29, v19
	s_waitcnt vmcnt(4)
	v_mul_f32_e32 v174, v30, v20
	s_waitcnt vmcnt(3)
	v_mul_f32_e32 v176, v31, v21
	v_pk_fma_f32 v[18:19], v[4:5], v[132:133], v[160:161] op_sel_hi:[0,1,1]
	v_mov_b32_e32 v20, v122
	v_mov_b32_e32 v21, v134
	v_pk_fma_f32 v[18:19], v[26:27], v[20:21], v[18:19] op_sel_hi:[0,1,1]
	v_mov_b32_e32 v134, v123
	s_waitcnt lgkmcnt(0)
	v_pk_mul_f32 v[172:173], v[28:29], v[22:23]
	ds_read_b128 v[148:151], v17 offset:1584
	v_pk_fma_f32 v[22:23], v[38:39], v[134:135], v[18:19] op_sel_hi:[0,1,1]
	ds_read_b128 v[18:21], v17 offset:288
	v_pk_mul_f32 v[178:179], v[30:31], v[24:25]
	v_mov_b32_e32 v24, v124
	v_mov_b32_e32 v40, v29
	v_mov_b32_e32 v42, v31
	s_waitcnt lgkmcnt(0)
	v_mov_b32_e32 v25, v18
	v_pk_fma_f32 v[22:23], v[28:29], v[24:25], v[22:23] op_sel_hi:[0,1,1]
	v_mov_b32_e32 v18, v125
	v_pk_fma_f32 v[18:19], v[40:41], v[18:19], v[22:23] op_sel_hi:[0,1,1]
	v_mov_b32_e32 v22, v126
	v_mov_b32_e32 v23, v20
	v_pk_fma_f32 v[18:19], v[30:31], v[22:23], v[18:19] op_sel_hi:[0,1,1]
	v_mov_b32_e32 v20, v127
	ds_read_b128 v[152:155], v17 offset:1840
	v_pk_fma_f32 v[22:23], v[42:43], v[20:21], v[18:19] op_sel_hi:[0,1,1]
	ds_read_b128 v[18:21], v17 offset:304
	v_mov_b32_e32 v24, v128
	s_waitcnt vmcnt(1)
	v_mov_b32_e32 v44, v33
	v_mov_b32_e32 v121, v141
	v_mov_b32_e32 v141, v166
	s_waitcnt lgkmcnt(0)
	v_mov_b32_e32 v25, v18
	v_pk_fma_f32 v[22:23], v[32:33], v[24:25], v[22:23] op_sel_hi:[0,1,1]
	v_mov_b32_e32 v18, v129
	v_pk_fma_f32 v[18:19], v[44:45], v[18:19], v[22:23] op_sel_hi:[0,1,1]
	v_mov_b32_e32 v22, v130
	v_mov_b32_e32 v23, v20
	s_waitcnt vmcnt(0)
	v_pk_fma_f32 v[18:19], v[34:35], v[22:23], v[18:19] op_sel_hi:[0,1,1]
	v_mov_b32_e32 v20, v131
	v_pk_fma_f32 v[20:21], v[36:37], v[20:21], v[18:19] op_sel_hi:[0,1,1]
	v_pk_fma_f32 v[18:19], v[4:5], v[136:137], v[162:163] op_sel_hi:[0,1,1]
	v_mov_b32_e32 v22, v118
	v_mov_b32_e32 v23, v138
	v_pk_fma_f32 v[18:19], v[26:27], v[22:23], v[18:19] op_sel_hi:[0,1,1]
	v_mov_b32_e32 v138, v119
	ds_read_b128 v[22:25], v17 offset:544
	ds_read_b128 v[116:119], v17 offset:800
	v_pk_fma_f32 v[18:19], v[38:39], v[138:139], v[18:19] op_sel_hi:[0,1,1]
	v_mov_b32_e32 v159, v167
	v_mov_b32_e32 v169, v172
	s_waitcnt lgkmcnt(1)
	v_mov_b32_e32 v122, v22
	s_waitcnt lgkmcnt(0)
	v_mov_b32_e32 v123, v116
	v_pk_fma_f32 v[18:19], v[28:29], v[122:123], v[18:19] op_sel_hi:[0,1,1]
	v_mov_b32_e32 v116, v23
	v_pk_fma_f32 v[18:19], v[40:41], v[116:117], v[18:19] op_sel_hi:[0,1,1]
	v_mov_b32_e32 v22, v24
	v_mov_b32_e32 v23, v118
	v_pk_fma_f32 v[18:19], v[30:31], v[22:23], v[18:19] op_sel_hi:[0,1,1]
	v_mov_b32_e32 v118, v25
	v_pk_fma_f32 v[18:19], v[42:43], v[118:119], v[18:19] op_sel_hi:[0,1,1]
	ds_read_b128 v[22:25], v17 offset:560
	ds_read_b128 v[116:119], v17 offset:816
	v_mov_b32_e32 v171, v173
	v_mov_b32_e32 v175, v178
	v_pk_mul_f32 v[152:153], v[32:33], v[152:153]
	s_waitcnt lgkmcnt(1)
	v_mov_b32_e32 v122, v22
	s_waitcnt lgkmcnt(0)
	v_mov_b32_e32 v123, v116
	v_pk_fma_f32 v[18:19], v[32:33], v[122:123], v[18:19] op_sel_hi:[0,1,1]
	v_mov_b32_e32 v116, v23
	v_pk_fma_f32 v[18:19], v[44:45], v[116:117], v[18:19] op_sel_hi:[0,1,1]
	v_mov_b32_e32 v22, v24
	v_mov_b32_e32 v23, v118
	v_pk_fma_f32 v[18:19], v[34:35], v[22:23], v[18:19] op_sel_hi:[0,1,1]
	v_mov_b32_e32 v118, v25
	v_pk_fma_f32 v[22:23], v[36:37], v[118:119], v[18:19] op_sel_hi:[0,1,1]
	v_pk_fma_f32 v[18:19], v[4:5], v[144:145], v[164:165] op_sel_hi:[0,1,1]
	v_mov_b32_e32 v24, v142
	v_mov_b32_e32 v25, v146
	v_pk_fma_f32 v[18:19], v[26:27], v[24:25], v[18:19] op_sel_hi:[0,1,1]
	ds_read_b128 v[24:27], v17 offset:1056
	ds_read_b128 v[116:119], v17 offset:1312
	v_mov_b32_e32 v146, v143
	v_pk_fma_f32 v[18:19], v[38:39], v[146:147], v[18:19] op_sel_hi:[0,1,1]
	v_mov_b32_e32 v177, v179
	s_waitcnt lgkmcnt(1)
	v_mov_b32_e32 v122, v24
	s_waitcnt lgkmcnt(0)
	v_mov_b32_e32 v123, v116
	v_pk_fma_f32 v[18:19], v[28:29], v[122:123], v[18:19] op_sel_hi:[0,1,1]
	v_mov_b32_e32 v116, v25
	v_pk_fma_f32 v[18:19], v[40:41], v[116:117], v[18:19] op_sel_hi:[0,1,1]
	v_mov_b32_e32 v24, v26
	v_mov_b32_e32 v25, v118
	v_pk_fma_f32 v[18:19], v[30:31], v[24:25], v[18:19] op_sel_hi:[0,1,1]
	v_mov_b32_e32 v118, v27
	ds_read_b128 v[24:27], v17 offset:1072
	ds_read_b128 v[28:31], v17 offset:1328
	v_pk_fma_f32 v[18:19], v[42:43], v[118:119], v[18:19] op_sel_hi:[0,1,1]
	v_mul_f32_e32 v148, v32, v148
	v_mul_f32_e32 v180, v33, v149
	s_waitcnt lgkmcnt(1)
	v_mov_b32_e32 v116, v24
	s_waitcnt lgkmcnt(0)
	v_mov_b32_e32 v117, v28
	v_pk_fma_f32 v[18:19], v[32:33], v[116:117], v[18:19] op_sel_hi:[0,1,1]
	v_mov_b32_e32 v28, v25
	v_pk_fma_f32 v[18:19], v[44:45], v[28:29], v[18:19] op_sel_hi:[0,1,1]
	v_pk_add_f32 v[28:29], v[156:157], v[120:121]
	v_mov_b32_e32 v24, v26
	v_pk_add_f32 v[28:29], v[28:29], v[140:141]
	v_mov_b32_e32 v25, v30
	v_pk_add_f32 v[28:29], v[28:29], v[158:159]
	v_pk_fma_f32 v[18:19], v[34:35], v[24:25], v[18:19] op_sel_hi:[0,1,1]
	v_pk_add_f32 v[28:29], v[28:29], v[168:169]
	v_mov_b32_e32 v35, v36
	v_pk_add_f32 v[28:29], v[28:29], v[170:171]
	v_mov_b32_e32 v149, v152
	v_pk_add_f32 v[28:29], v[28:29], v[174:175]
	v_mov_b32_e32 v30, v27
	v_pk_add_f32 v[28:29], v[28:29], v[176:177]
	v_pk_mul_f32 v[26:27], v[34:35], v[154:155]
	v_pk_add_f32 v[28:29], v[28:29], v[148:149]
	v_mov_b32_e32 v181, v153
	v_mul_f32_e32 v150, v34, v150
	v_pk_fma_f32 v[24:25], v[36:37], v[30:31], v[18:19] op_sel_hi:[0,1,1]
	v_mul_f32_e32 v18, v36, v151
	v_pk_add_f32 v[28:29], v[28:29], v[180:181]
	v_mov_b32_e32 v151, v26
	v_pk_add_f32 v[28:29], v[28:29], v[150:151]
	v_mov_b32_e32 v19, v27
	v_pk_add_f32 v[18:19], v[28:29], v[18:19]
	s_cbranch_scc1 .LBB0_50
	v_lshl_add_u32 v12, s13, 9, v48
	v_ashrrev_i32_e32 v13, 31, v12
	v_lshlrev_b64 v[14:15], 2, v[12:13]
	v_and_b32_e32 v4, 0x200, v12
	v_lshl_add_u64 v[16:17], s[14:15], 0, v[14:15]
	v_cmp_ne_u32_e32 vcc, 0, v4
	v_mul_f32_e32 v4, v20, v49
	v_lshl_add_u64 v[12:13], v[16:17], 0, s[46:47]
	s_and_b64 s[2:3], vcc, s[48:49]
	global_store_dword v[12:13], v4, off
	v_cndmask_b32_e64 v4, |v4|, 0, s[2:3]
	v_mul_f32_e32 v20, v21, v108
	v_lshl_add_u64 v[12:13], v[16:17], 0, s[50:51]
	global_store_dword v[12:13], v20, off
	v_add_f32_e64 v12, v4, |v20|
	s_and_b64 s[10:11], vcc, s[52:53]
	v_cndmask_b32_e64 v4, v12, v4, s[10:11]
	v_mul_f32_e32 v20, v22, v109
	v_lshl_add_u64 v[12:13], v[16:17], 0, s[54:55]
	global_store_dword v[12:13], v20, off
	v_add_f32_e64 v12, v4, |v20|
	v_cndmask_b32_e64 v4, v12, v4, s[10:11]
	v_mul_f32_e32 v20, v23, v110
	v_lshl_add_u64 v[12:13], v[16:17], 0, s[56:57]
	global_store_dword v[12:13], v20, off
	v_add_f32_e64 v12, v4, |v20|
	s_and_b64 s[10:11], vcc, s[58:59]
	v_cndmask_b32_e64 v4, v12, v4, s[10:11]
	v_mul_f32_e32 v20, v24, v111
	v_lshl_add_u64 v[12:13], v[16:17], 0, s[60:61]
	global_store_dword v[12:13], v20, off
	v_add_f32_e64 v12, v4, |v20|
	s_and_b64 s[10:11], vcc, s[62:63]
	v_cndmask_b32_e64 v4, v12, v4, s[10:11]
	v_mul_f32_e32 v20, v25, v112
	v_lshl_add_u64 v[12:13], v[16:17], 0, s[64:65]
	global_store_dword v[12:13], v20, off
	v_add_f32_e64 v12, v4, |v20|
	s_and_b64 s[10:11], vcc, s[66:67]
	v_cndmask_b32_e64 v4, v12, v4, s[10:11]
	v_mul_f32_e32 v18, v18, v113
	v_lshl_add_u64 v[12:13], v[16:17], 0, s[68:69]
	global_store_dword v[12:13], v18, off
	v_add_f32_e64 v12, v4, |v18|
	s_and_b64 s[10:11], vcc, s[70:71]
	v_cndmask_b32_e64 v4, v12, v4, s[10:11]
	v_mul_f32_e32 v18, v19, v114
	v_lshl_add_u64 v[12:13], v[16:17], 0, s[20:21]
	global_store_dword v[12:13], v18, off
	v_add_f32_e64 v12, v4, |v18|
	s_and_b64 vcc, vcc, s[72:73]
	v_cndmask_b32_e32 v4, v12, v4, vcc
	v_lshl_add_u64 v[12:13], s[44:45], 0, v[14:15]
	global_atomic_add_f32 v[12:13], v4, off
	s_add_i32 s13, s13, 1
	v_add_u32_e32 v115, 0x200, v115
	v_lshl_add_u64 v[8:9], v[8:9], 0, s[40:41]
	s_cmp_eq_u32 s13, 4
	v_lshl_add_u64 v[10:11], v[10:11], 0, s[40:41]
	s_cbranch_scc0 .LBB0_49
	s_add_i32 s94, s94, s95
	s_cmpk_lg_i32 s95, 0x100
	s_cbranch_scc1 .Lmlp_orig
	s_cmpk_lt_i32 s94, 0x400
	s_cbranch_scc1 .Lmlp_orig
	s_cmpk_ge_i32 s94, 0x500
	s_cbranch_scc1 .Lmlp_orig
	s_sub_i32 s94, s94, 0xe0
	s_cmpk_lt_i32 s94, 0x400
	s_cselect_b32 s94, 0x7fff, s94
.Lmlp_orig:
	s_cmpk_gt_i32 s94, 0x41f
	s_barrier
	s_cbranch_scc0 .LBB0_19
	s_branch .LBB0_54
